# final RMSNorm fused into the FFN2-down residual epilogue (16-wave rendezvous on the row sum-of-squares partials); the separate final-norm pass now covers the 256 sample rows only
# speedup vs baseline: 1.1156x; 1.0028x over previous
.LBB0_1492:
	s_load_dwordx2 s[92:93], s[0:1], 0x108
	v_lshrrev_b32_e32 v132, 6, v206
	v_and_b32_e32 v143, 63, v206
	v_lshrrev_b32_e32 v142, 2, v132
	v_and_b32_e32 v132, 3, v132
	v_readfirstlane_b32 s32, v142
	v_lshlrev_b32_e32 v142, 6, v142
	v_lshrrev_b32_e32 v146, 4, v143
	v_and_b32_e32 v212, 15, v143
	v_xor_b32_e32 v144, 16, v143
	v_xor_b32_e32 v145, 32, v143
	v_lshlrev_b32_e32 v144, 2, v144
	v_lshlrev_b32_e32 v145, 2, v145
	s_waitcnt lgkmcnt(0)
	s_lshl_b32 vcc_lo, s12, 8
	v_add_u32_e32 v142, vcc_lo, v142
	s_lshl_b32 vcc_lo, s49, 2
	v_add_u32_e32 v211, vcc_lo, v132
	v_add_u32_e32 v147, v142, v212
	v_lshlrev_b32_e32 v147, 6, v147
	v_lshl_add_u32 v211, v211, 2, v147
	v_lshlrev_b32_e32 v143, 5, v132
	v_lshrrev_b32_e32 v147, 3, v212
	v_lshl_add_u32 v147, v147, 2, v146
	v_lshl_add_u32 v143, v147, 2, v143
	v_lshlrev_b32_e32 v210, 3, v147
	s_lshl_b32 vcc_lo, s49, 8
	v_add_u32_e32 v143, vcc_lo, v143
	v_and_b32_e32 v147, 7, v212
	v_add_u32_e32 v142, v142, v147
	v_lshl_add_u32 v210, v142, 6, v210
	v_lshlrev_b32_e32 v148, 12, v142
	v_lshl_add_u32 v148, v143, 2, v148
	v_add_u32_e32 v149, 0x8000, v148
	v_lshlrev_b32_e32 v143, 2, v143
	v_mov_b32_e32 v213, 0
	s_mov_b32 s86, s94
	s_mov_b32 s87, s95
	s_mov_b32 s88, s94
	s_mov_b32 s89, s95
	s_add_u32 s100, s96, 0x5500000
	s_addc_u32 s101, s97, 0
	s_lshl_b32 vcc_lo, s12, 1
	s_add_u32 vcc_lo, vcc_lo, s32
	s_lshl_b32 vcc_lo, vcc_lo, 6
	s_add_u32 vcc_lo, vcc_lo, 0x8000
	s_add_u32 s90, s96, vcc_lo
	s_addc_u32 s91, s97, 0
	global_load_dwordx4 v[160:163], v148, s[86:87]
	global_load_dwordx4 v[164:167], v149, s[86:87]
	global_load_dwordx4 v[168:171], v148, s[86:87] offset:512
	global_load_dwordx4 v[172:175], v149, s[86:87] offset:512
	s_add_u32 s86, s86, 0x10000
	s_addc_u32 s87, s87, 0
	global_load_dwordx4 v[176:179], v148, s[86:87]
	global_load_dwordx4 v[180:183], v149, s[86:87]
	global_load_dwordx4 v[184:187], v148, s[86:87] offset:512
	global_load_dwordx4 v[188:191], v149, s[86:87] offset:512
	s_add_u32 s86, s86, 0x10000
	s_addc_u32 s87, s87, 0
	global_load_dwordx4 v[192:195], v148, s[86:87]
	global_load_dwordx4 v[196:199], v149, s[86:87]
	global_load_dwordx4 v[200:203], v148, s[86:87] offset:512
	v_mov_b32_e32 v156, v120
	v_mov_b32_e32 v157, v121
	v_mov_b32_e32 v158, v122
	v_mov_b32_e32 v159, v123
	v_mov_b32_dpp v120, v124 row_ror:8 row_mask:0xf bank_mask:0x3
	v_mov_b32_dpp v121, v125 row_ror:8 row_mask:0xf bank_mask:0x3
	v_mov_b32_dpp v122, v126 row_ror:8 row_mask:0xf bank_mask:0x3
	v_mov_b32_dpp v123, v127 row_ror:8 row_mask:0xf bank_mask:0x3
	v_mov_b32_dpp v124, v156 row_ror:8 row_mask:0xf bank_mask:0xc
	v_mov_b32_dpp v125, v157 row_ror:8 row_mask:0xf bank_mask:0xc
	v_mov_b32_dpp v126, v158 row_ror:8 row_mask:0xf bank_mask:0xc
	v_mov_b32_dpp v127, v159 row_ror:8 row_mask:0xf bank_mask:0xc
	s_waitcnt vmcnt(10)
	v_fma_f32 v124, v124, 0.5, v160
	v_fma_f32 v125, v125, 0.5, v161
	v_fma_f32 v126, v126, 0.5, v162
	v_fma_f32 v127, v127, 0.5, v163
	v_mul_f32_e32 v216, v124, v124
	v_fmac_f32_e32 v216, v125, v125
	v_fmac_f32_e32 v216, v126, v126
	v_fmac_f32_e32 v216, v127, v127
	global_load_dwordx4 v[160:163], v149, s[86:87] offset:512
	s_waitcnt vmcnt(10)
	v_fma_f32 v120, v120, 0.5, v164
	v_fma_f32 v121, v121, 0.5, v165
	v_fma_f32 v122, v122, 0.5, v166
	v_fma_f32 v123, v123, 0.5, v167
	v_mul_f32_e32 v217, v120, v120
	v_fmac_f32_e32 v217, v121, v121
	v_fmac_f32_e32 v217, v122, v122
	v_fmac_f32_e32 v217, v123, v123
	s_add_u32 s86, s86, 0x10000
	s_addc_u32 s87, s87, 0
	global_load_dwordx4 v[164:167], v148, s[86:87]
	v_mov_b32_e32 v156, v112
	v_mov_b32_e32 v157, v113
	v_mov_b32_e32 v158, v114
	v_mov_b32_e32 v159, v115
	v_mov_b32_dpp v112, v116 row_ror:8 row_mask:0xf bank_mask:0x3
	v_mov_b32_dpp v113, v117 row_ror:8 row_mask:0xf bank_mask:0x3
	v_mov_b32_dpp v114, v118 row_ror:8 row_mask:0xf bank_mask:0x3
	v_mov_b32_dpp v115, v119 row_ror:8 row_mask:0xf bank_mask:0x3
	v_mov_b32_dpp v116, v156 row_ror:8 row_mask:0xf bank_mask:0xc
	v_mov_b32_dpp v117, v157 row_ror:8 row_mask:0xf bank_mask:0xc
	v_mov_b32_dpp v118, v158 row_ror:8 row_mask:0xf bank_mask:0xc
	v_mov_b32_dpp v119, v159 row_ror:8 row_mask:0xf bank_mask:0xc
	s_waitcnt vmcnt(10)
	v_fma_f32 v116, v116, 0.5, v168
	v_fma_f32 v117, v117, 0.5, v169
	v_fma_f32 v118, v118, 0.5, v170
	v_fma_f32 v119, v119, 0.5, v171
	v_fmac_f32_e32 v216, v116, v116
	v_fmac_f32_e32 v216, v117, v117
	v_fmac_f32_e32 v216, v118, v118
	v_fmac_f32_e32 v216, v119, v119
	global_load_dwordx4 v[168:171], v149, s[86:87]
	s_waitcnt vmcnt(10)
	v_fma_f32 v112, v112, 0.5, v172
	v_fma_f32 v113, v113, 0.5, v173
	v_fma_f32 v114, v114, 0.5, v174
	v_fma_f32 v115, v115, 0.5, v175
	v_fmac_f32_e32 v217, v112, v112
	v_fmac_f32_e32 v217, v113, v113
	v_fmac_f32_e32 v217, v114, v114
	v_fmac_f32_e32 v217, v115, v115
	global_load_dwordx4 v[172:175], v148, s[86:87] offset:512
	s_nop 1
	v_add_f32_dpp v216, v216, v216 row_ror:8 row_mask:0xf bank_mask:0xf
	v_add_f32_dpp v217, v217, v217 row_ror:8 row_mask:0xf bank_mask:0xf
	s_nop 0
	ds_bpermute_b32 v147, v144, v216
	ds_bpermute_b32 v132, v144, v217
	s_waitcnt lgkmcnt(0)
	v_add_f32_e32 v216, v216, v147
	v_add_f32_e32 v217, v217, v132
	s_nop 0
	ds_bpermute_b32 v147, v145, v216
	ds_bpermute_b32 v132, v145, v217
	s_waitcnt lgkmcnt(0)
	v_add_f32_e32 v216, v216, v147
	v_add_f32_e32 v217, v217, v132
	v_cmp_gt_u32_e32 vcc, 8, v212
	s_nop 1
	v_cndmask_b32_e32 v216, v217, v216, vcc
	v_cmp_eq_u32_e32 vcc, 0, v146
	s_and_saveexec_b64 s[98:99], vcc
	global_store_dword v211, v216, s[100:101]
	s_mov_b64 exec, s[98:99]
	s_add_u32 s100, s100, 0x400
	s_addc_u32 s101, s101, 0
	v_mov_b32_e32 v156, v104
	v_mov_b32_e32 v157, v105
	v_mov_b32_e32 v158, v106
	v_mov_b32_e32 v159, v107
	v_mov_b32_dpp v104, v108 row_ror:8 row_mask:0xf bank_mask:0x3
	v_mov_b32_dpp v105, v109 row_ror:8 row_mask:0xf bank_mask:0x3
	v_mov_b32_dpp v106, v110 row_ror:8 row_mask:0xf bank_mask:0x3
	v_mov_b32_dpp v107, v111 row_ror:8 row_mask:0xf bank_mask:0x3
	v_mov_b32_dpp v108, v156 row_ror:8 row_mask:0xf bank_mask:0xc
	v_mov_b32_dpp v109, v157 row_ror:8 row_mask:0xf bank_mask:0xc
	v_mov_b32_dpp v110, v158 row_ror:8 row_mask:0xf bank_mask:0xc
	v_mov_b32_dpp v111, v159 row_ror:8 row_mask:0xf bank_mask:0xc
	s_waitcnt vmcnt(11)
	v_fma_f32 v108, v108, 0.5, v176
	v_fma_f32 v109, v109, 0.5, v177
	v_fma_f32 v110, v110, 0.5, v178
	v_fma_f32 v111, v111, 0.5, v179
	v_mul_f32_e32 v216, v108, v108
	v_fmac_f32_e32 v216, v109, v109
	v_fmac_f32_e32 v216, v110, v110
	v_fmac_f32_e32 v216, v111, v111
	global_load_dwordx4 v[176:179], v149, s[86:87] offset:512
	s_waitcnt vmcnt(11)
	v_fma_f32 v104, v104, 0.5, v180
	v_fma_f32 v105, v105, 0.5, v181
	v_fma_f32 v106, v106, 0.5, v182
	v_fma_f32 v107, v107, 0.5, v183
	v_mul_f32_e32 v217, v104, v104
	v_fmac_f32_e32 v217, v105, v105
	v_fmac_f32_e32 v217, v106, v106
	v_fmac_f32_e32 v217, v107, v107
	s_add_u32 s86, s86, 0x50000
	s_addc_u32 s87, s87, 0
	global_load_dwordx4 v[180:183], v148, s[86:87]
	v_mov_b32_e32 v156, v96
	v_mov_b32_e32 v157, v97
	v_mov_b32_e32 v158, v98
	v_mov_b32_e32 v159, v99
	v_mov_b32_dpp v96, v100 row_ror:8 row_mask:0xf bank_mask:0x3
	v_mov_b32_dpp v97, v101 row_ror:8 row_mask:0xf bank_mask:0x3
	v_mov_b32_dpp v98, v102 row_ror:8 row_mask:0xf bank_mask:0x3
	v_mov_b32_dpp v99, v103 row_ror:8 row_mask:0xf bank_mask:0x3
	v_mov_b32_dpp v100, v156 row_ror:8 row_mask:0xf bank_mask:0xc
	v_mov_b32_dpp v101, v157 row_ror:8 row_mask:0xf bank_mask:0xc
	v_mov_b32_dpp v102, v158 row_ror:8 row_mask:0xf bank_mask:0xc
	v_mov_b32_dpp v103, v159 row_ror:8 row_mask:0xf bank_mask:0xc
	s_waitcnt vmcnt(11)
	v_fma_f32 v100, v100, 0.5, v184
	v_fma_f32 v101, v101, 0.5, v185
	v_fma_f32 v102, v102, 0.5, v186
	v_fma_f32 v103, v103, 0.5, v187
	v_fmac_f32_e32 v216, v100, v100
	v_fmac_f32_e32 v216, v101, v101
	v_fmac_f32_e32 v216, v102, v102
	v_fmac_f32_e32 v216, v103, v103
	global_load_dwordx4 v[184:187], v149, s[86:87]
	s_waitcnt vmcnt(11)
	v_fma_f32 v96, v96, 0.5, v188
	v_fma_f32 v97, v97, 0.5, v189
	v_fma_f32 v98, v98, 0.5, v190
	v_fma_f32 v99, v99, 0.5, v191
	v_fmac_f32_e32 v217, v96, v96
	v_fmac_f32_e32 v217, v97, v97
	v_fmac_f32_e32 v217, v98, v98
	v_fmac_f32_e32 v217, v99, v99
	global_load_dwordx4 v[188:191], v148, s[86:87] offset:512
	s_nop 1
	v_add_f32_dpp v216, v216, v216 row_ror:8 row_mask:0xf bank_mask:0xf
	v_add_f32_dpp v217, v217, v217 row_ror:8 row_mask:0xf bank_mask:0xf
	s_nop 0
	ds_bpermute_b32 v147, v144, v216
	ds_bpermute_b32 v132, v144, v217
	s_waitcnt lgkmcnt(0)
	v_add_f32_e32 v216, v216, v147
	v_add_f32_e32 v217, v217, v132
	s_nop 0
	ds_bpermute_b32 v147, v145, v216
	ds_bpermute_b32 v132, v145, v217
	s_waitcnt lgkmcnt(0)
	v_add_f32_e32 v216, v216, v147
	v_add_f32_e32 v217, v217, v132
	v_cmp_gt_u32_e32 vcc, 8, v212
	s_nop 1
	v_cndmask_b32_e32 v216, v217, v216, vcc
	v_cmp_eq_u32_e32 vcc, 0, v146
	s_and_saveexec_b64 s[98:99], vcc
	global_store_dword v211, v216, s[100:101]
	s_mov_b64 exec, s[98:99]
	s_add_u32 s100, s100, 0x400
	s_addc_u32 s101, s101, 0
	v_mov_b32_e32 v156, v88
	v_mov_b32_e32 v157, v89
	v_mov_b32_e32 v158, v90
	v_mov_b32_e32 v159, v91
	v_mov_b32_dpp v88, v92 row_ror:8 row_mask:0xf bank_mask:0x3
	v_mov_b32_dpp v89, v93 row_ror:8 row_mask:0xf bank_mask:0x3
	v_mov_b32_dpp v90, v94 row_ror:8 row_mask:0xf bank_mask:0x3
	v_mov_b32_dpp v91, v95 row_ror:8 row_mask:0xf bank_mask:0x3
	v_mov_b32_dpp v92, v156 row_ror:8 row_mask:0xf bank_mask:0xc
	v_mov_b32_dpp v93, v157 row_ror:8 row_mask:0xf bank_mask:0xc
	v_mov_b32_dpp v94, v158 row_ror:8 row_mask:0xf bank_mask:0xc
	v_mov_b32_dpp v95, v159 row_ror:8 row_mask:0xf bank_mask:0xc
	s_waitcnt vmcnt(12)
	v_fma_f32 v92, v92, 0.5, v192
	v_fma_f32 v93, v93, 0.5, v193
	v_fma_f32 v94, v94, 0.5, v194
	v_fma_f32 v95, v95, 0.5, v195
	v_mul_f32_e32 v216, v92, v92
	v_fmac_f32_e32 v216, v93, v93
	v_fmac_f32_e32 v216, v94, v94
	v_fmac_f32_e32 v216, v95, v95
	global_load_dwordx4 v[192:195], v149, s[86:87] offset:512
	s_waitcnt vmcnt(12)
	v_fma_f32 v88, v88, 0.5, v196
	v_fma_f32 v89, v89, 0.5, v197
	v_fma_f32 v90, v90, 0.5, v198
	v_fma_f32 v91, v91, 0.5, v199
	v_mul_f32_e32 v217, v88, v88
	v_fmac_f32_e32 v217, v89, v89
	v_fmac_f32_e32 v217, v90, v90
	v_fmac_f32_e32 v217, v91, v91
	s_add_u32 s86, s86, 0x10000
	s_addc_u32 s87, s87, 0
	global_load_dwordx4 v[196:199], v148, s[86:87]
	v_mov_b32_e32 v156, v80
	v_mov_b32_e32 v157, v81
	v_mov_b32_e32 v158, v82
	v_mov_b32_e32 v159, v83
	v_mov_b32_dpp v80, v84 row_ror:8 row_mask:0xf bank_mask:0x3
	v_mov_b32_dpp v81, v85 row_ror:8 row_mask:0xf bank_mask:0x3
	v_mov_b32_dpp v82, v86 row_ror:8 row_mask:0xf bank_mask:0x3
	v_mov_b32_dpp v83, v87 row_ror:8 row_mask:0xf bank_mask:0x3
	v_mov_b32_dpp v84, v156 row_ror:8 row_mask:0xf bank_mask:0xc
	v_mov_b32_dpp v85, v157 row_ror:8 row_mask:0xf bank_mask:0xc
	v_mov_b32_dpp v86, v158 row_ror:8 row_mask:0xf bank_mask:0xc
	v_mov_b32_dpp v87, v159 row_ror:8 row_mask:0xf bank_mask:0xc
	s_waitcnt vmcnt(12)
	v_fma_f32 v84, v84, 0.5, v200
	v_fma_f32 v85, v85, 0.5, v201
	v_fma_f32 v86, v86, 0.5, v202
	v_fma_f32 v87, v87, 0.5, v203
	v_fmac_f32_e32 v216, v84, v84
	v_fmac_f32_e32 v216, v85, v85
	v_fmac_f32_e32 v216, v86, v86
	v_fmac_f32_e32 v216, v87, v87
	global_load_dwordx4 v[200:203], v149, s[86:87]
	s_waitcnt vmcnt(12)
	v_fma_f32 v80, v80, 0.5, v160
	v_fma_f32 v81, v81, 0.5, v161
	v_fma_f32 v82, v82, 0.5, v162
	v_fma_f32 v83, v83, 0.5, v163
	v_fmac_f32_e32 v217, v80, v80
	v_fmac_f32_e32 v217, v81, v81
	v_fmac_f32_e32 v217, v82, v82
	v_fmac_f32_e32 v217, v83, v83
	global_load_dwordx4 v[160:163], v148, s[86:87] offset:512
	s_nop 1
	v_add_f32_dpp v216, v216, v216 row_ror:8 row_mask:0xf bank_mask:0xf
	v_add_f32_dpp v217, v217, v217 row_ror:8 row_mask:0xf bank_mask:0xf
	s_nop 0
	ds_bpermute_b32 v147, v144, v216
	ds_bpermute_b32 v132, v144, v217
	s_waitcnt lgkmcnt(0)
	v_add_f32_e32 v216, v216, v147
	v_add_f32_e32 v217, v217, v132
	s_nop 0
	ds_bpermute_b32 v147, v145, v216
	ds_bpermute_b32 v132, v145, v217
	s_waitcnt lgkmcnt(0)
	v_add_f32_e32 v216, v216, v147
	v_add_f32_e32 v217, v217, v132
	v_cmp_gt_u32_e32 vcc, 8, v212
	s_nop 1
	v_cndmask_b32_e32 v216, v217, v216, vcc
	v_cmp_eq_u32_e32 vcc, 0, v146
	s_and_saveexec_b64 s[98:99], vcc
	global_store_dword v211, v216, s[100:101]
	s_mov_b64 exec, s[98:99]
	s_add_u32 s100, s100, 0x400
	s_addc_u32 s101, s101, 0
	v_mov_b32_e32 v156, v72
	v_mov_b32_e32 v157, v73
	v_mov_b32_e32 v158, v74
	v_mov_b32_e32 v159, v75
	v_mov_b32_dpp v72, v76 row_ror:8 row_mask:0xf bank_mask:0x3
	v_mov_b32_dpp v73, v77 row_ror:8 row_mask:0xf bank_mask:0x3
	v_mov_b32_dpp v74, v78 row_ror:8 row_mask:0xf bank_mask:0x3
	v_mov_b32_dpp v75, v79 row_ror:8 row_mask:0xf bank_mask:0x3
	v_mov_b32_dpp v76, v156 row_ror:8 row_mask:0xf bank_mask:0xc
	v_mov_b32_dpp v77, v157 row_ror:8 row_mask:0xf bank_mask:0xc
	v_mov_b32_dpp v78, v158 row_ror:8 row_mask:0xf bank_mask:0xc
	v_mov_b32_dpp v79, v159 row_ror:8 row_mask:0xf bank_mask:0xc
	s_waitcnt vmcnt(13)
	v_fma_f32 v76, v76, 0.5, v164
	v_fma_f32 v77, v77, 0.5, v165
	v_fma_f32 v78, v78, 0.5, v166
	v_fma_f32 v79, v79, 0.5, v167
	v_mul_f32_e32 v216, v76, v76
	v_fmac_f32_e32 v216, v77, v77
	v_fmac_f32_e32 v216, v78, v78
	v_fmac_f32_e32 v216, v79, v79
	global_load_dwordx4 v[164:167], v149, s[86:87] offset:512
	s_waitcnt vmcnt(13)
	v_fma_f32 v72, v72, 0.5, v168
	v_fma_f32 v73, v73, 0.5, v169
	v_fma_f32 v74, v74, 0.5, v170
	v_fma_f32 v75, v75, 0.5, v171
	v_mul_f32_e32 v217, v72, v72
	v_fmac_f32_e32 v217, v73, v73
	v_fmac_f32_e32 v217, v74, v74
	v_fmac_f32_e32 v217, v75, v75
	s_add_u32 s86, s86, 0x10000
	s_addc_u32 s87, s87, 0
	global_load_dwordx4 v[168:171], v148, s[86:87]
	v_mov_b32_e32 v156, v64
	v_mov_b32_e32 v157, v65
	v_mov_b32_e32 v158, v66
	v_mov_b32_e32 v159, v67
	v_mov_b32_dpp v64, v68 row_ror:8 row_mask:0xf bank_mask:0x3
	v_mov_b32_dpp v65, v69 row_ror:8 row_mask:0xf bank_mask:0x3
	v_mov_b32_dpp v66, v70 row_ror:8 row_mask:0xf bank_mask:0x3
	v_mov_b32_dpp v67, v71 row_ror:8 row_mask:0xf bank_mask:0x3
	v_mov_b32_dpp v68, v156 row_ror:8 row_mask:0xf bank_mask:0xc
	v_mov_b32_dpp v69, v157 row_ror:8 row_mask:0xf bank_mask:0xc
	v_mov_b32_dpp v70, v158 row_ror:8 row_mask:0xf bank_mask:0xc
	v_mov_b32_dpp v71, v159 row_ror:8 row_mask:0xf bank_mask:0xc
	s_waitcnt vmcnt(13)
	v_fma_f32 v68, v68, 0.5, v172
	v_fma_f32 v69, v69, 0.5, v173
	v_fma_f32 v70, v70, 0.5, v174
	v_fma_f32 v71, v71, 0.5, v175
	v_fmac_f32_e32 v216, v68, v68
	v_fmac_f32_e32 v216, v69, v69
	v_fmac_f32_e32 v216, v70, v70
	v_fmac_f32_e32 v216, v71, v71
	global_load_dwordx4 v[172:175], v149, s[86:87]
	s_waitcnt vmcnt(12)
	v_fma_f32 v64, v64, 0.5, v176
	v_fma_f32 v65, v65, 0.5, v177
	v_fma_f32 v66, v66, 0.5, v178
	v_fma_f32 v67, v67, 0.5, v179
	v_fmac_f32_e32 v217, v64, v64
	v_fmac_f32_e32 v217, v65, v65
	v_fmac_f32_e32 v217, v66, v66
	v_fmac_f32_e32 v217, v67, v67
	global_load_dwordx4 v[176:179], v148, s[86:87] offset:512
	s_nop 1
	v_add_f32_dpp v216, v216, v216 row_ror:8 row_mask:0xf bank_mask:0xf
	v_add_f32_dpp v217, v217, v217 row_ror:8 row_mask:0xf bank_mask:0xf
	s_nop 0
	ds_bpermute_b32 v147, v144, v216
	ds_bpermute_b32 v132, v144, v217
	s_waitcnt lgkmcnt(0)
	v_add_f32_e32 v216, v216, v147
	v_add_f32_e32 v217, v217, v132
	s_nop 0
	ds_bpermute_b32 v147, v145, v216
	ds_bpermute_b32 v132, v145, v217
	s_waitcnt lgkmcnt(0)
	v_add_f32_e32 v216, v216, v147
	v_add_f32_e32 v217, v217, v132
	v_cmp_gt_u32_e32 vcc, 8, v212
	s_nop 1
	v_cndmask_b32_e32 v216, v217, v216, vcc
	v_cmp_eq_u32_e32 vcc, 0, v146
	s_and_saveexec_b64 s[98:99], vcc
	global_store_dword v211, v216, s[100:101]
	s_mov_b64 exec, s[98:99]
	s_add_u32 s100, s100, 0x1400
	s_addc_u32 s101, s101, 0
	v_mov_b32_e32 v156, v56
	v_mov_b32_e32 v157, v57
	v_mov_b32_e32 v158, v58
	v_mov_b32_e32 v159, v59
	v_mov_b32_dpp v56, v60 row_ror:8 row_mask:0xf bank_mask:0x3
	v_mov_b32_dpp v57, v61 row_ror:8 row_mask:0xf bank_mask:0x3
	v_mov_b32_dpp v58, v62 row_ror:8 row_mask:0xf bank_mask:0x3
	v_mov_b32_dpp v59, v63 row_ror:8 row_mask:0xf bank_mask:0x3
	v_mov_b32_dpp v60, v156 row_ror:8 row_mask:0xf bank_mask:0xc
	v_mov_b32_dpp v61, v157 row_ror:8 row_mask:0xf bank_mask:0xc
	v_mov_b32_dpp v62, v158 row_ror:8 row_mask:0xf bank_mask:0xc
	v_mov_b32_dpp v63, v159 row_ror:8 row_mask:0xf bank_mask:0xc
	s_waitcnt vmcnt(13)
	v_fma_f32 v60, v60, 0.5, v180
	v_fma_f32 v61, v61, 0.5, v181
	v_fma_f32 v62, v62, 0.5, v182
	v_fma_f32 v63, v63, 0.5, v183
	v_mul_f32_e32 v216, v60, v60
	v_fmac_f32_e32 v216, v61, v61
	v_fmac_f32_e32 v216, v62, v62
	v_fmac_f32_e32 v216, v63, v63
	global_load_dwordx4 v[180:183], v149, s[86:87] offset:512
	s_waitcnt vmcnt(13)
	v_fma_f32 v56, v56, 0.5, v184
	v_fma_f32 v57, v57, 0.5, v185
	v_fma_f32 v58, v58, 0.5, v186
	v_fma_f32 v59, v59, 0.5, v187
	v_mul_f32_e32 v217, v56, v56
	v_fmac_f32_e32 v217, v57, v57
	v_fmac_f32_e32 v217, v58, v58
	v_fmac_f32_e32 v217, v59, v59
	s_add_u32 s86, s86, 0x10000
	s_addc_u32 s87, s87, 0
	global_load_dwordx4 v[184:187], v148, s[86:87]
	v_mov_b32_e32 v156, v48
	v_mov_b32_e32 v157, v49
	v_mov_b32_e32 v158, v50
	v_mov_b32_e32 v159, v51
	v_mov_b32_dpp v48, v52 row_ror:8 row_mask:0xf bank_mask:0x3
	v_mov_b32_dpp v49, v53 row_ror:8 row_mask:0xf bank_mask:0x3
	v_mov_b32_dpp v50, v54 row_ror:8 row_mask:0xf bank_mask:0x3
	v_mov_b32_dpp v51, v55 row_ror:8 row_mask:0xf bank_mask:0x3
	v_mov_b32_dpp v52, v156 row_ror:8 row_mask:0xf bank_mask:0xc
	v_mov_b32_dpp v53, v157 row_ror:8 row_mask:0xf bank_mask:0xc
	v_mov_b32_dpp v54, v158 row_ror:8 row_mask:0xf bank_mask:0xc
	v_mov_b32_dpp v55, v159 row_ror:8 row_mask:0xf bank_mask:0xc
	s_waitcnt vmcnt(13)
	v_fma_f32 v52, v52, 0.5, v188
	v_fma_f32 v53, v53, 0.5, v189
	v_fma_f32 v54, v54, 0.5, v190
	v_fma_f32 v55, v55, 0.5, v191
	v_fmac_f32_e32 v216, v52, v52
	v_fmac_f32_e32 v216, v53, v53
	v_fmac_f32_e32 v216, v54, v54
	v_fmac_f32_e32 v216, v55, v55
	global_load_dwordx4 v[188:191], v149, s[86:87]
	s_waitcnt vmcnt(12)
	v_fma_f32 v48, v48, 0.5, v192
	v_fma_f32 v49, v49, 0.5, v193
	v_fma_f32 v50, v50, 0.5, v194
	v_fma_f32 v51, v51, 0.5, v195
	v_fmac_f32_e32 v217, v48, v48
	v_fmac_f32_e32 v217, v49, v49
	v_fmac_f32_e32 v217, v50, v50
	v_fmac_f32_e32 v217, v51, v51
	global_load_dwordx4 v[192:195], v148, s[86:87] offset:512
	s_nop 1
	v_add_f32_dpp v216, v216, v216 row_ror:8 row_mask:0xf bank_mask:0xf
	v_add_f32_dpp v217, v217, v217 row_ror:8 row_mask:0xf bank_mask:0xf
	s_nop 0
	ds_bpermute_b32 v147, v144, v216
	ds_bpermute_b32 v132, v144, v217
	s_waitcnt lgkmcnt(0)
	v_add_f32_e32 v216, v216, v147
	v_add_f32_e32 v217, v217, v132
	s_nop 0
	ds_bpermute_b32 v147, v145, v216
	ds_bpermute_b32 v132, v145, v217
	s_waitcnt lgkmcnt(0)
	v_add_f32_e32 v216, v216, v147
	v_add_f32_e32 v217, v217, v132
	v_cmp_gt_u32_e32 vcc, 8, v212
	s_nop 1
	v_cndmask_b32_e32 v216, v217, v216, vcc
	v_cmp_eq_u32_e32 vcc, 0, v146
	s_and_saveexec_b64 s[98:99], vcc
	global_store_dword v211, v216, s[100:101]
	s_mov_b64 exec, s[98:99]
	s_add_u32 s100, s100, 0x400
	s_addc_u32 s101, s101, 0
	v_mov_b32_e32 v156, v40
	v_mov_b32_e32 v157, v41
	v_mov_b32_e32 v158, v42
	v_mov_b32_e32 v159, v43
	v_mov_b32_dpp v40, v44 row_ror:8 row_mask:0xf bank_mask:0x3
	v_mov_b32_dpp v41, v45 row_ror:8 row_mask:0xf bank_mask:0x3
	v_mov_b32_dpp v42, v46 row_ror:8 row_mask:0xf bank_mask:0x3
	v_mov_b32_dpp v43, v47 row_ror:8 row_mask:0xf bank_mask:0x3
	v_mov_b32_dpp v44, v156 row_ror:8 row_mask:0xf bank_mask:0xc
	v_mov_b32_dpp v45, v157 row_ror:8 row_mask:0xf bank_mask:0xc
	v_mov_b32_dpp v46, v158 row_ror:8 row_mask:0xf bank_mask:0xc
	v_mov_b32_dpp v47, v159 row_ror:8 row_mask:0xf bank_mask:0xc
	s_waitcnt vmcnt(13)
	v_fma_f32 v44, v44, 0.5, v196
	v_fma_f32 v45, v45, 0.5, v197
	v_fma_f32 v46, v46, 0.5, v198
	v_fma_f32 v47, v47, 0.5, v199
	v_mul_f32_e32 v216, v44, v44
	v_fmac_f32_e32 v216, v45, v45
	v_fmac_f32_e32 v216, v46, v46
	v_fmac_f32_e32 v216, v47, v47
	global_load_dwordx4 v[196:199], v149, s[86:87] offset:512
	s_waitcnt vmcnt(13)
	v_fma_f32 v40, v40, 0.5, v200
	v_fma_f32 v41, v41, 0.5, v201
	v_fma_f32 v42, v42, 0.5, v202
	v_fma_f32 v43, v43, 0.5, v203
	v_mul_f32_e32 v217, v40, v40
	v_fmac_f32_e32 v217, v41, v41
	v_fmac_f32_e32 v217, v42, v42
	v_fmac_f32_e32 v217, v43, v43
	v_mov_b32_e32 v156, v32
	v_mov_b32_e32 v157, v33
	v_mov_b32_e32 v158, v34
	v_mov_b32_e32 v159, v35
	v_mov_b32_dpp v32, v36 row_ror:8 row_mask:0xf bank_mask:0x3
	v_mov_b32_dpp v33, v37 row_ror:8 row_mask:0xf bank_mask:0x3
	v_mov_b32_dpp v34, v38 row_ror:8 row_mask:0xf bank_mask:0x3
	v_mov_b32_dpp v35, v39 row_ror:8 row_mask:0xf bank_mask:0x3
	v_mov_b32_dpp v36, v156 row_ror:8 row_mask:0xf bank_mask:0xc
	v_mov_b32_dpp v37, v157 row_ror:8 row_mask:0xf bank_mask:0xc
	v_mov_b32_dpp v38, v158 row_ror:8 row_mask:0xf bank_mask:0xc
	v_mov_b32_dpp v39, v159 row_ror:8 row_mask:0xf bank_mask:0xc
	s_waitcnt vmcnt(12)
	v_fma_f32 v36, v36, 0.5, v160
	v_fma_f32 v37, v37, 0.5, v161
	v_fma_f32 v38, v38, 0.5, v162
	v_fma_f32 v39, v39, 0.5, v163
	v_fmac_f32_e32 v216, v36, v36
	v_fmac_f32_e32 v216, v37, v37
	v_fmac_f32_e32 v216, v38, v38
	v_fmac_f32_e32 v216, v39, v39
	s_waitcnt vmcnt(10)
	v_fma_f32 v32, v32, 0.5, v164
	v_fma_f32 v33, v33, 0.5, v165
	v_fma_f32 v34, v34, 0.5, v166
	v_fma_f32 v35, v35, 0.5, v167
	v_fmac_f32_e32 v217, v32, v32
	v_fmac_f32_e32 v217, v33, v33
	v_fmac_f32_e32 v217, v34, v34
	v_fmac_f32_e32 v217, v35, v35
	s_nop 1
	v_add_f32_dpp v216, v216, v216 row_ror:8 row_mask:0xf bank_mask:0xf
	v_add_f32_dpp v217, v217, v217 row_ror:8 row_mask:0xf bank_mask:0xf
	s_nop 0
	ds_bpermute_b32 v147, v144, v216
	ds_bpermute_b32 v132, v144, v217
	s_waitcnt lgkmcnt(0)
	v_add_f32_e32 v216, v216, v147
	v_add_f32_e32 v217, v217, v132
	s_nop 0
	ds_bpermute_b32 v147, v145, v216
	ds_bpermute_b32 v132, v145, v217
	s_waitcnt lgkmcnt(0)
	v_add_f32_e32 v216, v216, v147
	v_add_f32_e32 v217, v217, v132
	v_cmp_gt_u32_e32 vcc, 8, v212
	s_nop 1
	v_cndmask_b32_e32 v216, v217, v216, vcc
	v_cmp_eq_u32_e32 vcc, 0, v146
	s_and_saveexec_b64 s[98:99], vcc
	global_store_dword v211, v216, s[100:101]
	s_mov_b64 exec, s[98:99]
	s_add_u32 s100, s100, 0x400
	s_addc_u32 s101, s101, 0
	v_mov_b32_e32 v156, v24
	v_mov_b32_e32 v157, v25
	v_mov_b32_e32 v158, v26
	v_mov_b32_e32 v159, v27
	v_mov_b32_dpp v24, v28 row_ror:8 row_mask:0xf bank_mask:0x3
	v_mov_b32_dpp v25, v29 row_ror:8 row_mask:0xf bank_mask:0x3
	v_mov_b32_dpp v26, v30 row_ror:8 row_mask:0xf bank_mask:0x3
	v_mov_b32_dpp v27, v31 row_ror:8 row_mask:0xf bank_mask:0x3
	v_mov_b32_dpp v28, v156 row_ror:8 row_mask:0xf bank_mask:0xc
	v_mov_b32_dpp v29, v157 row_ror:8 row_mask:0xf bank_mask:0xc
	v_mov_b32_dpp v30, v158 row_ror:8 row_mask:0xf bank_mask:0xc
	v_mov_b32_dpp v31, v159 row_ror:8 row_mask:0xf bank_mask:0xc
	s_waitcnt vmcnt(10)
	v_fma_f32 v28, v28, 0.5, v168
	v_fma_f32 v29, v29, 0.5, v169
	v_fma_f32 v30, v30, 0.5, v170
	v_fma_f32 v31, v31, 0.5, v171
	v_mul_f32_e32 v216, v28, v28
	v_fmac_f32_e32 v216, v29, v29
	v_fmac_f32_e32 v216, v30, v30
	v_fmac_f32_e32 v216, v31, v31
	s_waitcnt vmcnt(9)
	v_fma_f32 v24, v24, 0.5, v172
	v_fma_f32 v25, v25, 0.5, v173
	v_fma_f32 v26, v26, 0.5, v174
	v_fma_f32 v27, v27, 0.5, v175
	v_mul_f32_e32 v217, v24, v24
	v_fmac_f32_e32 v217, v25, v25
	v_fmac_f32_e32 v217, v26, v26
	v_fmac_f32_e32 v217, v27, v27
	v_mov_b32_e32 v156, v16
	v_mov_b32_e32 v157, v17
	v_mov_b32_e32 v158, v18
	v_mov_b32_e32 v159, v19
	v_mov_b32_dpp v16, v20 row_ror:8 row_mask:0xf bank_mask:0x3
	v_mov_b32_dpp v17, v21 row_ror:8 row_mask:0xf bank_mask:0x3
	v_mov_b32_dpp v18, v22 row_ror:8 row_mask:0xf bank_mask:0x3
	v_mov_b32_dpp v19, v23 row_ror:8 row_mask:0xf bank_mask:0x3
	v_mov_b32_dpp v20, v156 row_ror:8 row_mask:0xf bank_mask:0xc
	v_mov_b32_dpp v21, v157 row_ror:8 row_mask:0xf bank_mask:0xc
	v_mov_b32_dpp v22, v158 row_ror:8 row_mask:0xf bank_mask:0xc
	v_mov_b32_dpp v23, v159 row_ror:8 row_mask:0xf bank_mask:0xc
	s_waitcnt vmcnt(8)
	v_fma_f32 v20, v20, 0.5, v176
	v_fma_f32 v21, v21, 0.5, v177
	v_fma_f32 v22, v22, 0.5, v178
	v_fma_f32 v23, v23, 0.5, v179
	v_fmac_f32_e32 v216, v20, v20
	v_fmac_f32_e32 v216, v21, v21
	v_fmac_f32_e32 v216, v22, v22
	v_fmac_f32_e32 v216, v23, v23
	s_waitcnt vmcnt(6)
	v_fma_f32 v16, v16, 0.5, v180
	v_fma_f32 v17, v17, 0.5, v181
	v_fma_f32 v18, v18, 0.5, v182
	v_fma_f32 v19, v19, 0.5, v183
	v_fmac_f32_e32 v217, v16, v16
	v_fmac_f32_e32 v217, v17, v17
	v_fmac_f32_e32 v217, v18, v18
	v_fmac_f32_e32 v217, v19, v19
	s_nop 1
	v_add_f32_dpp v216, v216, v216 row_ror:8 row_mask:0xf bank_mask:0xf
	v_add_f32_dpp v217, v217, v217 row_ror:8 row_mask:0xf bank_mask:0xf
	s_nop 0
	ds_bpermute_b32 v147, v144, v216
	ds_bpermute_b32 v132, v144, v217
	s_waitcnt lgkmcnt(0)
	v_add_f32_e32 v216, v216, v147
	v_add_f32_e32 v217, v217, v132
	s_nop 0
	ds_bpermute_b32 v147, v145, v216
	ds_bpermute_b32 v132, v145, v217
	s_waitcnt lgkmcnt(0)
	v_add_f32_e32 v216, v216, v147
	v_add_f32_e32 v217, v217, v132
	v_cmp_gt_u32_e32 vcc, 8, v212
	s_nop 1
	v_cndmask_b32_e32 v216, v217, v216, vcc
	v_cmp_eq_u32_e32 vcc, 0, v146
	s_and_saveexec_b64 s[98:99], vcc
	global_store_dword v211, v216, s[100:101]
	s_mov_b64 exec, s[98:99]
	s_add_u32 s100, s100, 0x400
	s_addc_u32 s101, s101, 0
	v_mov_b32_e32 v156, v8
	v_mov_b32_e32 v157, v9
	v_mov_b32_e32 v158, v10
	v_mov_b32_e32 v159, v11
	v_mov_b32_dpp v8, v12 row_ror:8 row_mask:0xf bank_mask:0x3
	v_mov_b32_dpp v9, v13 row_ror:8 row_mask:0xf bank_mask:0x3
	v_mov_b32_dpp v10, v14 row_ror:8 row_mask:0xf bank_mask:0x3
	v_mov_b32_dpp v11, v15 row_ror:8 row_mask:0xf bank_mask:0x3
	v_mov_b32_dpp v12, v156 row_ror:8 row_mask:0xf bank_mask:0xc
	v_mov_b32_dpp v13, v157 row_ror:8 row_mask:0xf bank_mask:0xc
	v_mov_b32_dpp v14, v158 row_ror:8 row_mask:0xf bank_mask:0xc
	v_mov_b32_dpp v15, v159 row_ror:8 row_mask:0xf bank_mask:0xc
	s_waitcnt vmcnt(6)
	v_fma_f32 v12, v12, 0.5, v184
	v_fma_f32 v13, v13, 0.5, v185
	v_fma_f32 v14, v14, 0.5, v186
	v_fma_f32 v15, v15, 0.5, v187
	v_mul_f32_e32 v216, v12, v12
	v_fmac_f32_e32 v216, v13, v13
	v_fmac_f32_e32 v216, v14, v14
	v_fmac_f32_e32 v216, v15, v15
	s_waitcnt vmcnt(5)
	v_fma_f32 v8, v8, 0.5, v188
	v_fma_f32 v9, v9, 0.5, v189
	v_fma_f32 v10, v10, 0.5, v190
	v_fma_f32 v11, v11, 0.5, v191
	v_mul_f32_e32 v217, v8, v8
	v_fmac_f32_e32 v217, v9, v9
	v_fmac_f32_e32 v217, v10, v10
	v_fmac_f32_e32 v217, v11, v11
	v_mov_b32_e32 v156, v0
	v_mov_b32_e32 v157, v1
	v_mov_b32_e32 v158, v2
	v_mov_b32_e32 v159, v3
	v_mov_b32_dpp v0, v4 row_ror:8 row_mask:0xf bank_mask:0x3
	v_mov_b32_dpp v1, v5 row_ror:8 row_mask:0xf bank_mask:0x3
	v_mov_b32_dpp v2, v6 row_ror:8 row_mask:0xf bank_mask:0x3
	v_mov_b32_dpp v3, v7 row_ror:8 row_mask:0xf bank_mask:0x3
	v_mov_b32_dpp v4, v156 row_ror:8 row_mask:0xf bank_mask:0xc
	v_mov_b32_dpp v5, v157 row_ror:8 row_mask:0xf bank_mask:0xc
	v_mov_b32_dpp v6, v158 row_ror:8 row_mask:0xf bank_mask:0xc
	v_mov_b32_dpp v7, v159 row_ror:8 row_mask:0xf bank_mask:0xc
	s_waitcnt vmcnt(4)
	v_fma_f32 v4, v4, 0.5, v192
	v_fma_f32 v5, v5, 0.5, v193
	v_fma_f32 v6, v6, 0.5, v194
	v_fma_f32 v7, v7, 0.5, v195
	v_fmac_f32_e32 v216, v4, v4
	v_fmac_f32_e32 v216, v5, v5
	v_fmac_f32_e32 v216, v6, v6
	v_fmac_f32_e32 v216, v7, v7
	s_waitcnt vmcnt(2)
	v_fma_f32 v0, v0, 0.5, v196
	v_fma_f32 v1, v1, 0.5, v197
	v_fma_f32 v2, v2, 0.5, v198
	v_fma_f32 v3, v3, 0.5, v199
	v_fmac_f32_e32 v217, v0, v0
	v_fmac_f32_e32 v217, v1, v1
	v_fmac_f32_e32 v217, v2, v2
	v_fmac_f32_e32 v217, v3, v3
	s_nop 1
	v_add_f32_dpp v216, v216, v216 row_ror:8 row_mask:0xf bank_mask:0xf
	v_add_f32_dpp v217, v217, v217 row_ror:8 row_mask:0xf bank_mask:0xf
	s_nop 0
	ds_bpermute_b32 v147, v144, v216
	ds_bpermute_b32 v132, v144, v217
	s_waitcnt lgkmcnt(0)
	v_add_f32_e32 v216, v216, v147
	v_add_f32_e32 v217, v217, v132
	s_nop 0
	ds_bpermute_b32 v147, v145, v216
	ds_bpermute_b32 v132, v145, v217
	s_waitcnt lgkmcnt(0)
	v_add_f32_e32 v216, v216, v147
	v_add_f32_e32 v217, v217, v132
	v_cmp_gt_u32_e32 vcc, 8, v212
	s_nop 1
	v_cndmask_b32_e32 v216, v217, v216, vcc
	v_cmp_eq_u32_e32 vcc, 0, v146
	s_and_saveexec_b64 s[98:99], vcc
	global_store_dword v211, v216, s[100:101]
	s_mov_b64 exec, s[98:99]
	s_waitcnt vmcnt(0) lgkmcnt(0)
	v_mov_b32_e32 v132, 1
	s_mov_b64 s[98:99], exec
	s_mov_b64 exec, 1
	global_atomic_add v213, v132, s[90:91]
	s_mov_b64 exec, s[98:99]
	global_load_dwordx4 v[192:195], v143, s[92:93]
	global_load_dwordx4 v[196:199], v143, s[92:93] offset:512
	s_mov_b32 s32, 0x8000
.Lfz_p11_spin:
	global_load_dword v132, v213, s[90:91] sc1
	s_waitcnt vmcnt(0)
	v_readfirstlane_b32 vcc_lo, v132
	s_cmp_ge_u32 vcc_lo, 16
	s_cbranch_scc1 .Lfz_p11_met
	s_sleep 2
	s_sub_u32 s32, s32, 1
	s_cmp_lg_u32 s32, 0
	s_cbranch_scc1 .Lfz_p11_spin
.Lfz_p11_met:
	buffer_inv sc1
	s_add_u32 s100, s96, 0x5500000
	s_addc_u32 s101, s97, 0
	global_load_dwordx2 v[160:161], v210, s[100:101]
	global_load_dwordx2 v[162:163], v210, s[100:101] offset:512
	s_add_u32 s100, s100, 0x400
	s_addc_u32 s101, s101, 0
	global_load_dwordx2 v[164:165], v210, s[100:101]
	global_load_dwordx2 v[166:167], v210, s[100:101] offset:512
	s_add_u32 s100, s100, 0x400
	s_addc_u32 s101, s101, 0
	global_load_dwordx2 v[168:169], v210, s[100:101]
	global_load_dwordx2 v[170:171], v210, s[100:101] offset:512
	s_add_u32 s100, s100, 0x400
	s_addc_u32 s101, s101, 0
	global_load_dwordx2 v[172:173], v210, s[100:101]
	global_load_dwordx2 v[174:175], v210, s[100:101] offset:512
	s_add_u32 s100, s100, 0x1400
	s_addc_u32 s101, s101, 0
	global_load_dwordx2 v[176:177], v210, s[100:101]
	global_load_dwordx2 v[178:179], v210, s[100:101] offset:512
	s_add_u32 s100, s100, 0x400
	s_addc_u32 s101, s101, 0
	global_load_dwordx2 v[180:181], v210, s[100:101]
	global_load_dwordx2 v[182:183], v210, s[100:101] offset:512
	s_add_u32 s100, s100, 0x400
	s_addc_u32 s101, s101, 0
	global_load_dwordx2 v[184:185], v210, s[100:101]
	global_load_dwordx2 v[186:187], v210, s[100:101] offset:512
	s_add_u32 s100, s100, 0x400
	s_addc_u32 s101, s101, 0
	global_load_dwordx2 v[188:189], v210, s[100:101]
	global_load_dwordx2 v[190:191], v210, s[100:101] offset:512
	v_mov_b32_e32 v211, 0x358637bd
	s_waitcnt vmcnt(14)
	v_add_f32_e32 v216, v160, v161
	v_add_f32_e32 v217, v162, v163
	s_nop 1
	v_add_f32_dpp v216, v216, v216 row_ror:8 row_mask:0xf bank_mask:0xf
	v_add_f32_dpp v217, v217, v217 row_ror:8 row_mask:0xf bank_mask:0xf
	s_nop 0
	ds_bpermute_b32 v147, v144, v216
	ds_bpermute_b32 v132, v144, v217
	s_waitcnt lgkmcnt(0)
	v_add_f32_e32 v216, v216, v147
	v_add_f32_e32 v217, v217, v132
	s_nop 0
	ds_bpermute_b32 v147, v145, v216
	ds_bpermute_b32 v132, v145, v217
	s_waitcnt lgkmcnt(0)
	v_add_f32_e32 v216, v216, v147
	v_add_f32_e32 v217, v217, v132
	s_mov_b32 vcc_lo, 0x3a800000
	v_fma_f32 v216, v216, vcc_lo, v211
	v_fma_f32 v217, v217, vcc_lo, v211
	v_rsq_f32_e32 v216, v216
	v_rsq_f32_e32 v217, v217
	v_mul_f32_e32 v124, v124, v216
	v_mul_f32_e32 v125, v125, v216
	v_mul_f32_e32 v126, v126, v216
	v_mul_f32_e32 v127, v127, v216
	v_mul_f32_e32 v124, v124, v192
	v_mul_f32_e32 v125, v125, v193
	v_mul_f32_e32 v126, v126, v194
	v_mul_f32_e32 v127, v127, v195
	global_store_dwordx4 v148, v[124:127], s[88:89]
	v_mul_f32_e32 v120, v120, v217
	v_mul_f32_e32 v121, v121, v217
	v_mul_f32_e32 v122, v122, v217
	v_mul_f32_e32 v123, v123, v217
	v_mul_f32_e32 v120, v120, v192
	v_mul_f32_e32 v121, v121, v193
	v_mul_f32_e32 v122, v122, v194
	v_mul_f32_e32 v123, v123, v195
	global_store_dwordx4 v149, v[120:123], s[88:89]
	v_mul_f32_e32 v116, v116, v216
	v_mul_f32_e32 v117, v117, v216
	v_mul_f32_e32 v118, v118, v216
	v_mul_f32_e32 v119, v119, v216
	v_mul_f32_e32 v116, v116, v196
	v_mul_f32_e32 v117, v117, v197
	v_mul_f32_e32 v118, v118, v198
	v_mul_f32_e32 v119, v119, v199
	global_store_dwordx4 v148, v[116:119], s[88:89] offset:512
	v_mul_f32_e32 v112, v112, v217
	v_mul_f32_e32 v113, v113, v217
	v_mul_f32_e32 v114, v114, v217
	v_mul_f32_e32 v115, v115, v217
	v_mul_f32_e32 v112, v112, v196
	v_mul_f32_e32 v113, v113, v197
	v_mul_f32_e32 v114, v114, v198
	v_mul_f32_e32 v115, v115, v199
	global_store_dwordx4 v149, v[112:115], s[88:89] offset:512
	s_waitcnt vmcnt(16)
	v_add_f32_e32 v216, v164, v165
	v_add_f32_e32 v217, v166, v167
	s_nop 1
	v_add_f32_dpp v216, v216, v216 row_ror:8 row_mask:0xf bank_mask:0xf
	v_add_f32_dpp v217, v217, v217 row_ror:8 row_mask:0xf bank_mask:0xf
	s_nop 0
	ds_bpermute_b32 v147, v144, v216
	ds_bpermute_b32 v132, v144, v217
	s_waitcnt lgkmcnt(0)
	v_add_f32_e32 v216, v216, v147
	v_add_f32_e32 v217, v217, v132
	s_nop 0
	ds_bpermute_b32 v147, v145, v216
	ds_bpermute_b32 v132, v145, v217
	s_waitcnt lgkmcnt(0)
	v_add_f32_e32 v216, v216, v147
	v_add_f32_e32 v217, v217, v132
	s_mov_b32 vcc_lo, 0x3a800000
	v_fma_f32 v216, v216, vcc_lo, v211
	v_fma_f32 v217, v217, vcc_lo, v211
	v_rsq_f32_e32 v216, v216
	v_rsq_f32_e32 v217, v217
	s_add_u32 s88, s88, 0x10000
	s_addc_u32 s89, s89, 0
	v_mul_f32_e32 v108, v108, v216
	v_mul_f32_e32 v109, v109, v216
	v_mul_f32_e32 v110, v110, v216
	v_mul_f32_e32 v111, v111, v216
	v_mul_f32_e32 v108, v108, v192
	v_mul_f32_e32 v109, v109, v193
	v_mul_f32_e32 v110, v110, v194
	v_mul_f32_e32 v111, v111, v195
	global_store_dwordx4 v148, v[108:111], s[88:89]
	v_mul_f32_e32 v104, v104, v217
	v_mul_f32_e32 v105, v105, v217
	v_mul_f32_e32 v106, v106, v217
	v_mul_f32_e32 v107, v107, v217
	v_mul_f32_e32 v104, v104, v192
	v_mul_f32_e32 v105, v105, v193
	v_mul_f32_e32 v106, v106, v194
	v_mul_f32_e32 v107, v107, v195
	global_store_dwordx4 v149, v[104:107], s[88:89]
	v_mul_f32_e32 v100, v100, v216
	v_mul_f32_e32 v101, v101, v216
	v_mul_f32_e32 v102, v102, v216
	v_mul_f32_e32 v103, v103, v216
	v_mul_f32_e32 v100, v100, v196
	v_mul_f32_e32 v101, v101, v197
	v_mul_f32_e32 v102, v102, v198
	v_mul_f32_e32 v103, v103, v199
	global_store_dwordx4 v148, v[100:103], s[88:89] offset:512
	v_mul_f32_e32 v96, v96, v217
	v_mul_f32_e32 v97, v97, v217
	v_mul_f32_e32 v98, v98, v217
	v_mul_f32_e32 v99, v99, v217
	v_mul_f32_e32 v96, v96, v196
	v_mul_f32_e32 v97, v97, v197
	v_mul_f32_e32 v98, v98, v198
	v_mul_f32_e32 v99, v99, v199
	global_store_dwordx4 v149, v[96:99], s[88:89] offset:512
	s_waitcnt vmcnt(18)
	v_add_f32_e32 v216, v168, v169
	v_add_f32_e32 v217, v170, v171
	s_nop 1
	v_add_f32_dpp v216, v216, v216 row_ror:8 row_mask:0xf bank_mask:0xf
	v_add_f32_dpp v217, v217, v217 row_ror:8 row_mask:0xf bank_mask:0xf
	s_nop 0
	ds_bpermute_b32 v147, v144, v216
	ds_bpermute_b32 v132, v144, v217
	s_waitcnt lgkmcnt(0)
	v_add_f32_e32 v216, v216, v147
	v_add_f32_e32 v217, v217, v132
	s_nop 0
	ds_bpermute_b32 v147, v145, v216
	ds_bpermute_b32 v132, v145, v217
	s_waitcnt lgkmcnt(0)
	v_add_f32_e32 v216, v216, v147
	v_add_f32_e32 v217, v217, v132
	s_mov_b32 vcc_lo, 0x3a800000
	v_fma_f32 v216, v216, vcc_lo, v211
	v_fma_f32 v217, v217, vcc_lo, v211
	v_rsq_f32_e32 v216, v216
	v_rsq_f32_e32 v217, v217
	s_add_u32 s88, s88, 0x10000
	s_addc_u32 s89, s89, 0
	v_mul_f32_e32 v92, v92, v216
	v_mul_f32_e32 v93, v93, v216
	v_mul_f32_e32 v94, v94, v216
	v_mul_f32_e32 v95, v95, v216
	v_mul_f32_e32 v92, v92, v192
	v_mul_f32_e32 v93, v93, v193
	v_mul_f32_e32 v94, v94, v194
	v_mul_f32_e32 v95, v95, v195
	global_store_dwordx4 v148, v[92:95], s[88:89]
	v_mul_f32_e32 v88, v88, v217
	v_mul_f32_e32 v89, v89, v217
	v_mul_f32_e32 v90, v90, v217
	v_mul_f32_e32 v91, v91, v217
	v_mul_f32_e32 v88, v88, v192
	v_mul_f32_e32 v89, v89, v193
	v_mul_f32_e32 v90, v90, v194
	v_mul_f32_e32 v91, v91, v195
	global_store_dwordx4 v149, v[88:91], s[88:89]
	v_mul_f32_e32 v84, v84, v216
	v_mul_f32_e32 v85, v85, v216
	v_mul_f32_e32 v86, v86, v216
	v_mul_f32_e32 v87, v87, v216
	v_mul_f32_e32 v84, v84, v196
	v_mul_f32_e32 v85, v85, v197
	v_mul_f32_e32 v86, v86, v198
	v_mul_f32_e32 v87, v87, v199
	global_store_dwordx4 v148, v[84:87], s[88:89] offset:512
	v_mul_f32_e32 v80, v80, v217
	v_mul_f32_e32 v81, v81, v217
	v_mul_f32_e32 v82, v82, v217
	v_mul_f32_e32 v83, v83, v217
	v_mul_f32_e32 v80, v80, v196
	v_mul_f32_e32 v81, v81, v197
	v_mul_f32_e32 v82, v82, v198
	v_mul_f32_e32 v83, v83, v199
	global_store_dwordx4 v149, v[80:83], s[88:89] offset:512
	s_waitcnt vmcnt(20)
	v_add_f32_e32 v216, v172, v173
	v_add_f32_e32 v217, v174, v175
	s_nop 1
	v_add_f32_dpp v216, v216, v216 row_ror:8 row_mask:0xf bank_mask:0xf
	v_add_f32_dpp v217, v217, v217 row_ror:8 row_mask:0xf bank_mask:0xf
	s_nop 0
	ds_bpermute_b32 v147, v144, v216
	ds_bpermute_b32 v132, v144, v217
	s_waitcnt lgkmcnt(0)
	v_add_f32_e32 v216, v216, v147
	v_add_f32_e32 v217, v217, v132
	s_nop 0
	ds_bpermute_b32 v147, v145, v216
	ds_bpermute_b32 v132, v145, v217
	s_waitcnt lgkmcnt(0)
	v_add_f32_e32 v216, v216, v147
	v_add_f32_e32 v217, v217, v132
	s_mov_b32 vcc_lo, 0x3a800000
	v_fma_f32 v216, v216, vcc_lo, v211
	v_fma_f32 v217, v217, vcc_lo, v211
	v_rsq_f32_e32 v216, v216
	v_rsq_f32_e32 v217, v217
	s_add_u32 s88, s88, 0x10000
	s_addc_u32 s89, s89, 0
	v_mul_f32_e32 v76, v76, v216
	v_mul_f32_e32 v77, v77, v216
	v_mul_f32_e32 v78, v78, v216
	v_mul_f32_e32 v79, v79, v216
	v_mul_f32_e32 v76, v76, v192
	v_mul_f32_e32 v77, v77, v193
	v_mul_f32_e32 v78, v78, v194
	v_mul_f32_e32 v79, v79, v195
	global_store_dwordx4 v148, v[76:79], s[88:89]
	v_mul_f32_e32 v72, v72, v217
	v_mul_f32_e32 v73, v73, v217
	v_mul_f32_e32 v74, v74, v217
	v_mul_f32_e32 v75, v75, v217
	v_mul_f32_e32 v72, v72, v192
	v_mul_f32_e32 v73, v73, v193
	v_mul_f32_e32 v74, v74, v194
	v_mul_f32_e32 v75, v75, v195
	global_store_dwordx4 v149, v[72:75], s[88:89]
	v_mul_f32_e32 v68, v68, v216
	v_mul_f32_e32 v69, v69, v216
	v_mul_f32_e32 v70, v70, v216
	v_mul_f32_e32 v71, v71, v216
	v_mul_f32_e32 v68, v68, v196
	v_mul_f32_e32 v69, v69, v197
	v_mul_f32_e32 v70, v70, v198
	v_mul_f32_e32 v71, v71, v199
	global_store_dwordx4 v148, v[68:71], s[88:89] offset:512
	v_mul_f32_e32 v64, v64, v217
	v_mul_f32_e32 v65, v65, v217
	v_mul_f32_e32 v66, v66, v217
	v_mul_f32_e32 v67, v67, v217
	v_mul_f32_e32 v64, v64, v196
	v_mul_f32_e32 v65, v65, v197
	v_mul_f32_e32 v66, v66, v198
	v_mul_f32_e32 v67, v67, v199
	global_store_dwordx4 v149, v[64:67], s[88:89] offset:512
	s_waitcnt vmcnt(22)
	v_add_f32_e32 v216, v176, v177
	v_add_f32_e32 v217, v178, v179
	s_nop 1
	v_add_f32_dpp v216, v216, v216 row_ror:8 row_mask:0xf bank_mask:0xf
	v_add_f32_dpp v217, v217, v217 row_ror:8 row_mask:0xf bank_mask:0xf
	s_nop 0
	ds_bpermute_b32 v147, v144, v216
	ds_bpermute_b32 v132, v144, v217
	s_waitcnt lgkmcnt(0)
	v_add_f32_e32 v216, v216, v147
	v_add_f32_e32 v217, v217, v132
	s_nop 0
	ds_bpermute_b32 v147, v145, v216
	ds_bpermute_b32 v132, v145, v217
	s_waitcnt lgkmcnt(0)
	v_add_f32_e32 v216, v216, v147
	v_add_f32_e32 v217, v217, v132
	s_mov_b32 vcc_lo, 0x3a800000
	v_fma_f32 v216, v216, vcc_lo, v211
	v_fma_f32 v217, v217, vcc_lo, v211
	v_rsq_f32_e32 v216, v216
	v_rsq_f32_e32 v217, v217
	s_add_u32 s88, s88, 0x50000
	s_addc_u32 s89, s89, 0
	v_mul_f32_e32 v60, v60, v216
	v_mul_f32_e32 v61, v61, v216
	v_mul_f32_e32 v62, v62, v216
	v_mul_f32_e32 v63, v63, v216
	v_mul_f32_e32 v60, v60, v192
	v_mul_f32_e32 v61, v61, v193
	v_mul_f32_e32 v62, v62, v194
	v_mul_f32_e32 v63, v63, v195
	global_store_dwordx4 v148, v[60:63], s[88:89]
	v_mul_f32_e32 v56, v56, v217
	v_mul_f32_e32 v57, v57, v217
	v_mul_f32_e32 v58, v58, v217
	v_mul_f32_e32 v59, v59, v217
	v_mul_f32_e32 v56, v56, v192
	v_mul_f32_e32 v57, v57, v193
	v_mul_f32_e32 v58, v58, v194
	v_mul_f32_e32 v59, v59, v195
	global_store_dwordx4 v149, v[56:59], s[88:89]
	v_mul_f32_e32 v52, v52, v216
	v_mul_f32_e32 v53, v53, v216
	v_mul_f32_e32 v54, v54, v216
	v_mul_f32_e32 v55, v55, v216
	v_mul_f32_e32 v52, v52, v196
	v_mul_f32_e32 v53, v53, v197
	v_mul_f32_e32 v54, v54, v198
	v_mul_f32_e32 v55, v55, v199
	global_store_dwordx4 v148, v[52:55], s[88:89] offset:512
	v_mul_f32_e32 v48, v48, v217
	v_mul_f32_e32 v49, v49, v217
	v_mul_f32_e32 v50, v50, v217
	v_mul_f32_e32 v51, v51, v217
	v_mul_f32_e32 v48, v48, v196
	v_mul_f32_e32 v49, v49, v197
	v_mul_f32_e32 v50, v50, v198
	v_mul_f32_e32 v51, v51, v199
	global_store_dwordx4 v149, v[48:51], s[88:89] offset:512
	s_waitcnt vmcnt(24)
	v_add_f32_e32 v216, v180, v181
	v_add_f32_e32 v217, v182, v183
	s_nop 1
	v_add_f32_dpp v216, v216, v216 row_ror:8 row_mask:0xf bank_mask:0xf
	v_add_f32_dpp v217, v217, v217 row_ror:8 row_mask:0xf bank_mask:0xf
	s_nop 0
	ds_bpermute_b32 v147, v144, v216
	ds_bpermute_b32 v132, v144, v217
	s_waitcnt lgkmcnt(0)
	v_add_f32_e32 v216, v216, v147
	v_add_f32_e32 v217, v217, v132
	s_nop 0
	ds_bpermute_b32 v147, v145, v216
	ds_bpermute_b32 v132, v145, v217
	s_waitcnt lgkmcnt(0)
	v_add_f32_e32 v216, v216, v147
	v_add_f32_e32 v217, v217, v132
	s_mov_b32 vcc_lo, 0x3a800000
	v_fma_f32 v216, v216, vcc_lo, v211
	v_fma_f32 v217, v217, vcc_lo, v211
	v_rsq_f32_e32 v216, v216
	v_rsq_f32_e32 v217, v217
	s_add_u32 s88, s88, 0x10000
	s_addc_u32 s89, s89, 0
	v_mul_f32_e32 v44, v44, v216
	v_mul_f32_e32 v45, v45, v216
	v_mul_f32_e32 v46, v46, v216
	v_mul_f32_e32 v47, v47, v216
	v_mul_f32_e32 v44, v44, v192
	v_mul_f32_e32 v45, v45, v193
	v_mul_f32_e32 v46, v46, v194
	v_mul_f32_e32 v47, v47, v195
	global_store_dwordx4 v148, v[44:47], s[88:89]
	v_mul_f32_e32 v40, v40, v217
	v_mul_f32_e32 v41, v41, v217
	v_mul_f32_e32 v42, v42, v217
	v_mul_f32_e32 v43, v43, v217
	v_mul_f32_e32 v40, v40, v192
	v_mul_f32_e32 v41, v41, v193
	v_mul_f32_e32 v42, v42, v194
	v_mul_f32_e32 v43, v43, v195
	global_store_dwordx4 v149, v[40:43], s[88:89]
	v_mul_f32_e32 v36, v36, v216
	v_mul_f32_e32 v37, v37, v216
	v_mul_f32_e32 v38, v38, v216
	v_mul_f32_e32 v39, v39, v216
	v_mul_f32_e32 v36, v36, v196
	v_mul_f32_e32 v37, v37, v197
	v_mul_f32_e32 v38, v38, v198
	v_mul_f32_e32 v39, v39, v199
	global_store_dwordx4 v148, v[36:39], s[88:89] offset:512
	v_mul_f32_e32 v32, v32, v217
	v_mul_f32_e32 v33, v33, v217
	v_mul_f32_e32 v34, v34, v217
	v_mul_f32_e32 v35, v35, v217
	v_mul_f32_e32 v32, v32, v196
	v_mul_f32_e32 v33, v33, v197
	v_mul_f32_e32 v34, v34, v198
	v_mul_f32_e32 v35, v35, v199
	global_store_dwordx4 v149, v[32:35], s[88:89] offset:512
	s_waitcnt vmcnt(26)
	v_add_f32_e32 v216, v184, v185
	v_add_f32_e32 v217, v186, v187
	s_nop 1
	v_add_f32_dpp v216, v216, v216 row_ror:8 row_mask:0xf bank_mask:0xf
	v_add_f32_dpp v217, v217, v217 row_ror:8 row_mask:0xf bank_mask:0xf
	s_nop 0
	ds_bpermute_b32 v147, v144, v216
	ds_bpermute_b32 v132, v144, v217
	s_waitcnt lgkmcnt(0)
	v_add_f32_e32 v216, v216, v147
	v_add_f32_e32 v217, v217, v132
	s_nop 0
	ds_bpermute_b32 v147, v145, v216
	ds_bpermute_b32 v132, v145, v217
	s_waitcnt lgkmcnt(0)
	v_add_f32_e32 v216, v216, v147
	v_add_f32_e32 v217, v217, v132
	s_mov_b32 vcc_lo, 0x3a800000
	v_fma_f32 v216, v216, vcc_lo, v211
	v_fma_f32 v217, v217, vcc_lo, v211
	v_rsq_f32_e32 v216, v216
	v_rsq_f32_e32 v217, v217
	s_add_u32 s88, s88, 0x10000
	s_addc_u32 s89, s89, 0
	v_mul_f32_e32 v28, v28, v216
	v_mul_f32_e32 v29, v29, v216
	v_mul_f32_e32 v30, v30, v216
	v_mul_f32_e32 v31, v31, v216
	v_mul_f32_e32 v28, v28, v192
	v_mul_f32_e32 v29, v29, v193
	v_mul_f32_e32 v30, v30, v194
	v_mul_f32_e32 v31, v31, v195
	global_store_dwordx4 v148, v[28:31], s[88:89]
	v_mul_f32_e32 v24, v24, v217
	v_mul_f32_e32 v25, v25, v217
	v_mul_f32_e32 v26, v26, v217
	v_mul_f32_e32 v27, v27, v217
	v_mul_f32_e32 v24, v24, v192
	v_mul_f32_e32 v25, v25, v193
	v_mul_f32_e32 v26, v26, v194
	v_mul_f32_e32 v27, v27, v195
	global_store_dwordx4 v149, v[24:27], s[88:89]
	v_mul_f32_e32 v20, v20, v216
	v_mul_f32_e32 v21, v21, v216
	v_mul_f32_e32 v22, v22, v216
	v_mul_f32_e32 v23, v23, v216
	v_mul_f32_e32 v20, v20, v196
	v_mul_f32_e32 v21, v21, v197
	v_mul_f32_e32 v22, v22, v198
	v_mul_f32_e32 v23, v23, v199
	global_store_dwordx4 v148, v[20:23], s[88:89] offset:512
	v_mul_f32_e32 v16, v16, v217
	v_mul_f32_e32 v17, v17, v217
	v_mul_f32_e32 v18, v18, v217
	v_mul_f32_e32 v19, v19, v217
	v_mul_f32_e32 v16, v16, v196
	v_mul_f32_e32 v17, v17, v197
	v_mul_f32_e32 v18, v18, v198
	v_mul_f32_e32 v19, v19, v199
	global_store_dwordx4 v149, v[16:19], s[88:89] offset:512
	s_waitcnt vmcnt(28)
	v_add_f32_e32 v216, v188, v189
	v_add_f32_e32 v217, v190, v191
	s_nop 1
	v_add_f32_dpp v216, v216, v216 row_ror:8 row_mask:0xf bank_mask:0xf
	v_add_f32_dpp v217, v217, v217 row_ror:8 row_mask:0xf bank_mask:0xf
	s_nop 0
	ds_bpermute_b32 v147, v144, v216
	ds_bpermute_b32 v132, v144, v217
	s_waitcnt lgkmcnt(0)
	v_add_f32_e32 v216, v216, v147
	v_add_f32_e32 v217, v217, v132
	s_nop 0
	ds_bpermute_b32 v147, v145, v216
	ds_bpermute_b32 v132, v145, v217
	s_waitcnt lgkmcnt(0)
	v_add_f32_e32 v216, v216, v147
	v_add_f32_e32 v217, v217, v132
	s_mov_b32 vcc_lo, 0x3a800000
	v_fma_f32 v216, v216, vcc_lo, v211
	v_fma_f32 v217, v217, vcc_lo, v211
	v_rsq_f32_e32 v216, v216
	v_rsq_f32_e32 v217, v217
	s_add_u32 s88, s88, 0x10000
	s_addc_u32 s89, s89, 0
	v_mul_f32_e32 v12, v12, v216
	v_mul_f32_e32 v13, v13, v216
	v_mul_f32_e32 v14, v14, v216
	v_mul_f32_e32 v15, v15, v216
	v_mul_f32_e32 v12, v12, v192
	v_mul_f32_e32 v13, v13, v193
	v_mul_f32_e32 v14, v14, v194
	v_mul_f32_e32 v15, v15, v195
	global_store_dwordx4 v148, v[12:15], s[88:89]
	v_mul_f32_e32 v8, v8, v217
	v_mul_f32_e32 v9, v9, v217
	v_mul_f32_e32 v10, v10, v217
	v_mul_f32_e32 v11, v11, v217
	v_mul_f32_e32 v8, v8, v192
	v_mul_f32_e32 v9, v9, v193
	v_mul_f32_e32 v10, v10, v194
	v_mul_f32_e32 v11, v11, v195
	global_store_dwordx4 v149, v[8:11], s[88:89]
	v_mul_f32_e32 v4, v4, v216
	v_mul_f32_e32 v5, v5, v216
	v_mul_f32_e32 v6, v6, v216
	v_mul_f32_e32 v7, v7, v216
	v_mul_f32_e32 v4, v4, v196
	v_mul_f32_e32 v5, v5, v197
	v_mul_f32_e32 v6, v6, v198
	v_mul_f32_e32 v7, v7, v199
	global_store_dwordx4 v148, v[4:7], s[88:89] offset:512
	v_mul_f32_e32 v0, v0, v217
	v_mul_f32_e32 v1, v1, v217
	v_mul_f32_e32 v2, v2, v217
	v_mul_f32_e32 v3, v3, v217
	v_mul_f32_e32 v0, v0, v196
	v_mul_f32_e32 v1, v1, v197
	v_mul_f32_e32 v2, v2, v198
	v_mul_f32_e32 v3, v3, v199
	global_store_dwordx4 v149, v[0:3], s[88:89] offset:512
	s_and_b64 vcc, exec, s[8:9]
	s_mov_b64 s[8:9], -1
	s_cbranch_vccnz .LBB0_1477
	s_andn2_b64 vcc, exec, s[14:15]
	s_cbranch_vccnz .LBB0_1476
	s_barrier
	s_branch .LBB0_1476

.LBB0_1596:
	s_or_b64 exec, exec, s[2:3]
	s_waitcnt lgkmcnt(0)
	s_barrier
	s_nop 0
	v_lshrrev_b32_e32 v8, 6, v206
	v_and_b32_e32 v1, 63, v206
	s_load_dwordx2 s[88:89], s[0:1], 0x108
	v_readfirstlane_b32 s86, v8
	v_lshlrev_b32_e32 v2, 4, v1
	v_xor_b32_e32 v3, 1, v1
	v_lshlrev_b32_e32 v3, 2, v3
	v_xor_b32_e32 v4, 2, v1
	v_lshlrev_b32_e32 v4, 2, v4
	v_xor_b32_e32 v5, 4, v1
	v_lshlrev_b32_e32 v5, 2, v5
	v_xor_b32_e32 v6, 8, v1
	v_lshlrev_b32_e32 v6, 2, v6
	v_and_b32_e32 v7, 15, v1
	v_lshlrev_b32_e32 v7, 2, v7
	v_mov_b32_e32 v9, 0x358637bd
	s_add_u32 s87, s33, s86
	s_add_u32 s87, s87, 0x10000
	s_waitcnt lgkmcnt(0)
	global_load_dwordx4 v[16:19], v2, s[88:89]
	global_load_dwordx4 v[20:23], v2, s[88:89] offset:1024
	global_load_dwordx4 v[24:27], v2, s[88:89] offset:2048
	global_load_dwordx4 v[28:31], v2, s[88:89] offset:3072
	s_cmp_ge_u32 s87, 0x10100
	s_cbranch_scc1 .Lfn_done
	s_lshl_b32 s32, s87, 12
	s_add_u32 s90, s36, s32
	s_addc_u32 s91, s37, 0
	s_lshl_b32 s32, s87, 6
	s_add_u32 s94, s38, s32
	s_addc_u32 s95, s39, 0
	s_add_u32 s94, s94, 0x5500000
	s_addc_u32 s95, s95, 0
	global_load_dword v10, v7, s[94:95]
	global_load_dwordx4 v[32:35], v2, s[90:91]
	global_load_dwordx4 v[36:39], v2, s[90:91] offset:1024
	global_load_dwordx4 v[40:43], v2, s[90:91] offset:2048
	global_load_dwordx4 v[44:47], v2, s[90:91] offset:3072
